# v68: XCD-local seams: every workgroup polls the 64 arrival words itself (one 64-lane sc1 load per poll), no leader / release hop
# speedup vs baseline: 1.0048x; 1.0048x over previous
.LBB0_642:
	s_getreg_b32 s4, hwreg(HW_REG_XCC_ID, 0, 4)
	s_waitcnt vmcnt(0)
	s_barrier
	s_and_saveexec_b64 s[2:3], s[14:15]
	s_cbranch_execz .LBB0_694
	v_readlane_b32 s98, v255, 63
	s_nop 0
	s_cmp_lg_u32 s98, 0
	s_cbranch_scc1 .Llb_full_g2
	s_cmp_lg_u32 s33, 64
	s_cbranch_scc1 .Llb_full_g2
	buffer_inv sc1
	v_readlane_b32 s98, v255, 56
	v_readlane_b32 s100, v253, 1
	v_readlane_b32 s101, v253, 2
	v_readlane_b32 s99, v253, 0
	v_readlane_b32 vcc_lo, v254, 28
	s_add_i32 s98, s98, 1
	v_writelane_b32 v255, s98, 56
	s_lshl_b32 s99, s99, 14
	s_sub_u32 s100, s100, s99
	s_subb_u32 s101, s101, 0
	s_add_u32 s100, s100, 0xb000
	s_addc_u32 s101, s101, 0
	s_getreg_b32 s99, hwreg(HW_REG_XCC_ID, 0, 4)
	s_and_b32 s99, s99, 15
	s_lshl_b32 s99, s99, 8
	s_lshl_b32 vcc_hi, vcc_lo, 2
	s_add_i32 vcc_hi, vcc_hi, s99
	v_mov_b32_e32 v4, vcc_hi
	v_mov_b32_e32 v5, s98
	global_store_dword v4, v5, s[100:101]
	s_branch .Llb_lead_g2
	s_lshr_b32 s99, s99, 2
	v_mov_b32_e32 v4, s99
	s_mov_b32 s99, 0

.Llb_lrel_g2:
	s_mov_b64 exec, 1
.Llb_done_g2:
	s_waitcnt vmcnt(0)
	s_branch .LBB0_694

.LBB0_697:
	s_or_b64 exec, exec, s[2:3]
	s_getreg_b32 s4, hwreg(HW_REG_XCC_ID, 0, 4)
	s_waitcnt vmcnt(0)
	s_barrier
	s_and_saveexec_b64 s[2:3], s[14:15]
	s_cbranch_execz .LBB0_749
	v_readlane_b32 s98, v255, 63
	s_nop 0
	s_cmp_lg_u32 s98, 0
	s_cbranch_scc1 .Llb_full_ln1
	s_cmp_lg_u32 s33, 64
	s_cbranch_scc1 .Llb_full_ln1
	v_readlane_b32 s98, v255, 56
	v_readlane_b32 s100, v253, 1
	v_readlane_b32 s101, v253, 2
	v_readlane_b32 s99, v253, 0
	v_readlane_b32 vcc_lo, v254, 28
	s_add_i32 s98, s98, 1
	v_writelane_b32 v255, s98, 56
	s_lshl_b32 s99, s99, 14
	s_sub_u32 s100, s100, s99
	s_subb_u32 s101, s101, 0
	s_add_u32 s100, s100, 0xb000
	s_addc_u32 s101, s101, 0
	s_getreg_b32 s99, hwreg(HW_REG_XCC_ID, 0, 4)
	s_and_b32 s99, s99, 15
	s_lshl_b32 s99, s99, 8
	s_lshl_b32 vcc_hi, vcc_lo, 2
	s_add_i32 vcc_hi, vcc_hi, s99
	v_mov_b32_e32 v4, vcc_hi
	v_mov_b32_e32 v5, s98
	global_store_dword v4, v5, s[100:101]
	s_branch .Llb_lead_ln1
	s_lshr_b32 s99, s99, 2
	v_mov_b32_e32 v4, s99
	s_mov_b32 s99, 0

.Llb_lrel_ln1:
	s_mov_b64 exec, 1
.Llb_done_ln1:
	s_waitcnt vmcnt(0)
	s_branch .LBB0_749

.LBB0_780:
	s_getreg_b32 s2, hwreg(HW_REG_XCC_ID, 0, 4)
	s_waitcnt vmcnt(0)
	s_barrier
	s_and_saveexec_b64 s[0:1], s[14:15]
	s_cbranch_execz .LBB0_832
	v_readlane_b32 s98, v255, 63
	s_nop 0
	s_cmp_lg_u32 s98, 0
	s_cbranch_scc1 .Llb_full_g3
	s_cmp_lg_u32 s33, 64
	s_cbranch_scc1 .Llb_full_g3
	buffer_inv sc1
	v_readlane_b32 s98, v255, 56
	v_readlane_b32 s100, v253, 1
	v_readlane_b32 s101, v253, 2
	v_readlane_b32 s99, v253, 0
	v_readlane_b32 vcc_lo, v254, 28
	s_add_i32 s98, s98, 1
	v_writelane_b32 v255, s98, 56
	s_lshl_b32 s99, s99, 14
	s_sub_u32 s100, s100, s99
	s_subb_u32 s101, s101, 0
	s_add_u32 s100, s100, 0xb000
	s_addc_u32 s101, s101, 0
	s_getreg_b32 s99, hwreg(HW_REG_XCC_ID, 0, 4)
	s_and_b32 s99, s99, 15
	s_lshl_b32 s99, s99, 8
	s_lshl_b32 vcc_hi, vcc_lo, 2
	s_add_i32 vcc_hi, vcc_hi, s99
	v_mov_b32_e32 v4, vcc_hi
	v_mov_b32_e32 v5, s98
	global_store_dword v4, v5, s[100:101]
	s_branch .Llb_lead_g3
	s_lshr_b32 s99, s99, 2
	v_mov_b32_e32 v4, s99
	s_mov_b32 s99, 0

.Llb_lrel_g3:
	s_mov_b64 exec, 1
.Llb_done_g3:
	s_waitcnt vmcnt(0)
	s_branch .LBB0_832

.LBB0_875:
	s_or_b64 exec, exec, s[44:45]
	s_setprio 0
	s_andn2_b64 vcc, exec, s[30:31]
	v_readlane_b32 s34, v254, 58
	v_readlane_b32 s35, v254, 59
	s_cbranch_vccnz .LBB0_294
	s_getreg_b32 s2, hwreg(HW_REG_XCC_ID, 0, 4)
	s_waitcnt vmcnt(0)
	s_waitcnt lgkmcnt(0)
	s_barrier
	s_and_saveexec_b64 s[0:1], s[14:15]
	s_cbranch_execz .LBB0_293
	v_readlane_b32 s98, v255, 63
	s_nop 0
	s_cmp_lg_u32 s98, 0
	s_cbranch_scc1 .Llb_full_peer
	s_cmp_lg_u32 s33, 64
	s_cbranch_scc1 .Llb_full_peer
	v_readlane_b32 s98, v255, 56
	v_readlane_b32 s100, v253, 1
	v_readlane_b32 s101, v253, 2
	v_readlane_b32 s99, v253, 0
	v_readlane_b32 vcc_lo, v254, 28
	s_add_i32 s98, s98, 1
	v_writelane_b32 v255, s98, 56
	s_lshl_b32 s99, s99, 14
	s_sub_u32 s100, s100, s99
	s_subb_u32 s101, s101, 0
	s_add_u32 s100, s100, 0xb000
	s_addc_u32 s101, s101, 0
	s_getreg_b32 s99, hwreg(HW_REG_XCC_ID, 0, 4)
	s_and_b32 s99, s99, 15
	s_lshl_b32 s99, s99, 8
	s_lshl_b32 vcc_hi, vcc_lo, 2
	s_add_i32 vcc_hi, vcc_hi, s99
	v_mov_b32_e32 v4, vcc_hi
	v_mov_b32_e32 v5, s98
	global_store_dword v4, v5, s[100:101]
	s_branch .Llb_lead_peer
	s_lshr_b32 s99, s99, 2
	v_mov_b32_e32 v4, s99
	s_mov_b32 s99, 0

.Llb_lrel_peer:
	s_mov_b64 exec, 1
.Llb_done_peer:
	s_waitcnt vmcnt(0)
	s_branch .LBB0_293
